# attention B unit prologue: Q loads and tile-0 DMA issued before the wait for the bias loads
# speedup vs baseline: 1.0042x; 1.0042x over previous
.LBB0_380:
	s_and_b32 s30, s28, 7
	s_mul_i32 s4, s30, 0x201
	s_mov_b64 s[12:13], 0
	v_mov_b32_e32 v0, v111
	v_mov_b32_e32 v1, v110
	v_mov_b32_e32 v2, v215
	s_barrier
	v_mul_hi_u32 v3, v215, s21
	v_lshrrev_b32_e32 v3, 9, v3
	v_sub_u32_e32 v4, v110, v3
	v_mad_u32_u24 v4, v3, s22, v4
	v_med3_i32 v4, v4, s23, v114
	v_add_u32_e32 v4, s4, v4
	v_ashrrev_i32_e32 v5, 31, v4
	v_lshl_add_u64 v[4:5], v[4:5], 2, s[66:67]
	global_load_dword v16, v[4:5], off offset:1024
	v_add_u32_e32 v2, 0x200, v215
	v_mul_hi_u32 v3, v2, s21
	v_lshrrev_b32_e32 v3, 9, v3
	v_sub_u32_e32 v6, v110, v3
	v_add_u32_e32 v6, 0xfffffe00, v6
	v_mad_u32_u24 v6, v3, s22, v6
	v_med3_i32 v6, v6, s23, v114
	v_add_u32_e32 v6, s4, v6
	v_ashrrev_i32_e32 v7, 31, v6
	v_lshl_add_u64 v[6:7], v[6:7], 2, s[66:67]
	global_load_dword v17, v[6:7], off offset:1024
	v_add_u32_e32 v2, 0x400, v215
	v_mul_hi_u32 v3, v2, s21
	v_lshrrev_b32_e32 v3, 9, v3
	v_sub_u32_e32 v8, v110, v3
	v_add_u32_e32 v8, 0xfffffc00, v8
	v_mad_u32_u24 v8, v3, s22, v8
	v_med3_i32 v8, v8, s23, v114
	v_add_u32_e32 v8, s4, v8
	v_ashrrev_i32_e32 v9, 31, v8
	v_lshl_add_u64 v[8:9], v[8:9], 2, s[66:67]
	global_load_dword v18, v[8:9], off offset:1024
	v_add_u32_e32 v2, 0x600, v215
	v_mul_hi_u32 v3, v2, s21
	v_lshrrev_b32_e32 v3, 9, v3
	v_sub_u32_e32 v10, v110, v3
	v_add_u32_e32 v10, 0xfffffa00, v10
	v_mad_u32_u24 v10, v3, s22, v10
	v_med3_i32 v10, v10, s23, v114
	v_add_u32_e32 v10, s4, v10
	v_ashrrev_i32_e32 v11, 31, v10
	v_lshl_add_u64 v[10:11], v[10:11], 2, s[66:67]
	global_load_dword v19, v[10:11], off offset:1024
	v_add_u32_e32 v2, 0x800, v215
	v_mul_hi_u32 v3, v2, s21
	v_lshrrev_b32_e32 v3, 9, v3
	v_sub_u32_e32 v12, v110, v3
	v_add_u32_e32 v12, 0xfffff800, v12
	v_mad_u32_u24 v12, v3, s22, v12
	v_med3_i32 v12, v12, s23, v114
	v_add_u32_e32 v12, s4, v12
	v_ashrrev_i32_e32 v13, 31, v12
	v_lshl_add_u64 v[12:13], v[12:13], 2, s[66:67]
	global_load_dword v20, v[12:13], off offset:1024
	v_cmp_gt_u32_e32 vcc, 16, v215
	s_and_saveexec_b64 s[12:13], vcc
	v_add_u32_e32 v2, 0xa00, v215
	v_mul_hi_u32 v3, v2, s21
	v_lshrrev_b32_e32 v3, 9, v3
	v_sub_u32_e32 v14, v110, v3
	v_add_u32_e32 v14, 0xfffff600, v14
	v_mad_u32_u24 v14, v3, s22, v14
	v_med3_i32 v14, v14, s23, v114
	v_add_u32_e32 v14, s4, v14
	v_ashrrev_i32_e32 v15, 31, v14
	v_lshl_add_u64 v[14:15], v[14:15], 2, s[66:67]
	global_load_dword v21, v[14:15], off offset:1024
	s_or_b64 exec, exec, s[12:13]
	s_ashr_i32 s13, s28, 7
	s_lshl_b32 s37, s13, 8
	s_lshl_b32 s4, s28, 8
	s_add_i32 s37, s37, s40
	s_lshl_b32 s12, s13, 2
	s_and_b32 s31, s4, 0x7800
	s_ashr_i32 s29, s37, 31
	s_add_u32 s4, s37, s31
	s_addc_u32 s29, s29, 0
	s_mul_i32 s34, s29, 0x1800
	s_mul_hi_u32 s35, s4, 0x1800
	s_add_i32 s35, s35, s34
	s_mul_i32 s34, s4, 0x1800
	s_add_u32 s34, s10, s34
	s_addc_u32 s35, s11, s35
	s_lshl_b32 s36, s30, 7
	s_add_u32 s34, s34, s36
	s_addc_u32 s35, s35, 0
	v_lshl_add_u64 v[0:1], s[34:35], 0, v[132:133]
	v_lshl_add_u64 v[0:1], v[0:1], 0, v[134:135]
	global_load_dwordx4 v[64:67], v[0:1], off offset:3072
	global_load_dwordx4 v[68:71], v[0:1], off offset:3104
	global_load_dwordx4 v[72:75], v[0:1], off offset:3136
	global_load_dwordx4 v[76:79], v[0:1], off offset:3168
	s_mulk_i32 s31, 0x1800
	s_add_u32 s31, s10, s31
	s_addc_u32 s35, s11, 0
	s_add_u32 s31, s31, s36
	s_addc_u32 s35, s35, 0
	s_add_u32 s43, s31, 0x1000
	s_addc_u32 s44, s35, 0
	v_readfirstlane_b32 s34, v215
	s_add_u32 s36, s31, 0x1400
	s_addc_u32 s38, s35, 0
	s_max_i32 s42, s12, 8
	s_lshr_b32 s39, s34, 6
	s_add_i32 s35, s42, -8
	v_lshl_or_b32 v0, s39, 3, v172
	s_add_i32 s31, s12, 4
	v_lshrrev_b32_e32 v2, 1, v0
	s_mul_i32 s54, s35, 0x60000
	s_mul_hi_u32 s45, s35, 0x60000
	v_xor_b32_e32 v2, v2, v215
	s_add_u32 s52, s43, s54
	v_lshlrev_b32_e32 v2, 3, v2
	s_addc_u32 s53, s44, s45
	s_lshl_b32 s34, s39, 10
	v_mul_lo_u32 v3, v0, s18
	v_and_b32_e32 v32, 56, v2
	s_add_i32 s34, s34, 0
	v_or_b32_e32 v98, v32, v3
	s_add_u32 s54, s36, s54
	v_mov_b32_e32 v1, v99
	v_or_b32_e32 v0, v115, v3
	v_lshl_add_u64 v[2:3], v[98:99], 1, s[52:53]
	s_addc_u32 s55, s38, s45
	s_mov_b32 m0, s34
	v_lshl_add_u64 v[4:5], v[0:1], 1, s[54:55]
	s_add_i32 s45, s42, -7
	global_load_lds_dwordx4 v[2:3], off
	s_add_i32 m0, s34, 0x2000
	s_nop 0
	global_load_lds_dwordx4 v[4:5], off
	s_waitcnt vmcnt(6)
	v_mul_f32_e32 v16, 0x3fb8aa3b, v16
	ds_write_b32 v111, v16
	v_mul_f32_e32 v17, 0x3fb8aa3b, v17
	ds_write_b32 v111, v17 offset:2048
	v_mul_f32_e32 v18, 0x3fb8aa3b, v18
	ds_write_b32 v111, v18 offset:4096
	v_mul_f32_e32 v19, 0x3fb8aa3b, v19
	ds_write_b32 v111, v19 offset:6144
	v_mul_f32_e32 v20, 0x3fb8aa3b, v20
	ds_write_b32 v111, v20 offset:8192
	v_cmp_gt_u32_e32 vcc, 16, v215
	s_and_saveexec_b64 s[100:101], vcc
	v_mul_f32_e32 v21, 0x3fb8aa3b, v21
	ds_write_b32 v111, v21 offset:10240
	s_or_b64 exec, exec, s[100:101]
	s_barrier
	s_cmp_ge_i32 s45, s31
	s_cbranch_scc1 .LBB0_384
	s_mul_hi_u32 s54, s45, 0x60000
	s_mul_i32 s45, s45, 0x60000
	s_add_u32 s52, s43, s45
	s_addc_u32 s53, s44, s54
	s_add_i32 m0, s34, 0x4000
	v_lshl_add_u64 v[2:3], v[98:99], 1, s[52:53]
	s_add_u32 s52, s36, s45
	s_addc_u32 s53, s38, s54
	global_load_lds_dwordx4 v[2:3], off
	v_lshl_add_u64 v[2:3], v[0:1], 1, s[52:53]
	s_add_i32 m0, s34, 0x6000
	s_nop 0
	global_load_lds_dwordx4 v[2:3], off
